# v50 + sc1 write-through hint on GEMM epilogue stores and LN2 output stores
# speedup vs baseline: 1.0042x; 1.0042x over previous
.LBB0_1087:
	global_load_dwordx2 v[98:99], v[96:97], off nt
	global_load_dwordx2 v[100:101], v[96:97], off offset:512 nt
	global_load_dwordx2 v[102:103], v[96:97], off offset:1024 nt
	global_load_dwordx2 v[104:105], v[96:97], off offset:1536 nt
	global_load_dwordx2 v[106:107], v[96:97], off offset:2048 nt
	global_load_dwordx2 v[108:109], v[96:97], off offset:2560 nt
	global_load_dwordx2 v[110:111], v[96:97], off offset:3072 nt
	global_load_dwordx2 v[112:113], v[96:97], off offset:3584 nt
	v_add_co_u32_e32 v114, vcc, s10, v96
	s_add_i32 s2, s2, s4
	s_nop 0
	v_addc_co_u32_e32 v115, vcc, 0, v97, vcc
	ds_read_b128 v[64:67], v232
	global_load_dwordx2 v[116:117], v[114:115], off nt
	global_load_dwordx2 v[118:119], v[114:115], off offset:512 nt
	global_load_dwordx2 v[154:155], v[114:115], off offset:1024 nt
	global_load_dwordx2 v[164:165], v[114:115], off offset:1536 nt
	global_load_dwordx2 v[166:167], v[114:115], off offset:2048 nt
	global_load_dwordx2 v[176:177], v[114:115], off offset:2560 nt
	global_load_dwordx2 v[178:179], v[114:115], off offset:3072 nt
	global_load_dwordx2 v[180:181], v[114:115], off offset:3584 nt
	v_lshl_add_u64 v[96:97], v[96:97], 0, s[8:9]
	s_cmpk_lt_i32 s2, 0x4000
	s_waitcnt vmcnt(15)
	v_lshlrev_b32_e32 v163, 16, v99
	v_lshlrev_b32_e32 v162, 16, v98
	v_and_b32_e32 v183, 0xffff0000, v99
	v_and_b32_e32 v182, 0xffff0000, v98
	s_waitcnt vmcnt(14)
	v_lshlrev_b32_e32 v161, 16, v101
	v_lshlrev_b32_e32 v160, 16, v100
	v_and_b32_e32 v185, 0xffff0000, v101
	v_and_b32_e32 v184, 0xffff0000, v100
	v_pk_add_f32 v[190:191], v[162:163], v[182:183]
	v_pk_add_f32 v[192:193], v[160:161], v[184:185]
	s_waitcnt vmcnt(13)
	v_lshlrev_b32_e32 v156, 16, v102
	v_and_b32_e32 v157, 0xffff0000, v102
	v_lshlrev_b32_e32 v158, 16, v103
	v_and_b32_e32 v159, 0xffff0000, v103
	s_waitcnt vmcnt(12)
	v_and_b32_e32 v147, 0xffff0000, v104
	s_waitcnt vmcnt(7)
	v_lshlrev_b32_e32 v128, 16, v116
	v_and_b32_e32 v129, 0xffff0000, v116
	v_lshlrev_b32_e32 v130, 16, v117
	v_and_b32_e32 v131, 0xffff0000, v117
	s_waitcnt vmcnt(6)
	v_lshlrev_b32_e32 v122, 16, v118
	v_and_b32_e32 v123, 0xffff0000, v118
	v_lshlrev_b32_e32 v127, 16, v119
	v_and_b32_e32 v125, 0xffff0000, v119
	s_waitcnt vmcnt(4)
	v_lshlrev_b32_e32 v116, 16, v164
	v_and_b32_e32 v117, 0xffff0000, v164
	v_lshlrev_b32_e32 v118, 16, v165
	v_and_b32_e32 v119, 0xffff0000, v165
	v_add_f32_e32 v146, v190, v191
	v_pk_add_f32 v[164:165], v[192:193], v[192:193] op_sel:[0,1] op_sel_hi:[1,0]
	v_lshlrev_b32_e32 v149, 16, v104
	v_lshlrev_b32_e32 v153, 16, v105
	v_and_b32_e32 v151, 0xffff0000, v105
	v_add_f32_e32 v152, v156, v157
	v_add_f32_e32 v150, v158, v159
	v_add_f32_e32 v148, 0, v146
	v_mov_b32_e32 v165, v147
	v_lshlrev_b32_e32 v145, 16, v107
	v_lshlrev_b32_e32 v144, 16, v106
	v_and_b32_e32 v187, 0xffff0000, v107
	v_and_b32_e32 v186, 0xffff0000, v106
	v_lshlrev_b32_e32 v134, 16, v110
	v_and_b32_e32 v135, 0xffff0000, v110
	v_lshlrev_b32_e32 v139, 16, v111
	v_and_b32_e32 v137, 0xffff0000, v111
	v_lshlrev_b32_e32 v133, 16, v113
	v_and_b32_e32 v189, 0xffff0000, v113
	s_waitcnt vmcnt(3)
	v_lshlrev_b32_e32 v110, 16, v166
	v_and_b32_e32 v111, 0xffff0000, v166
	v_lshlrev_b32_e32 v115, 16, v167
	v_and_b32_e32 v113, 0xffff0000, v167
	v_pk_add_f32 v[166:167], v[152:153], v[150:151]
	v_pk_add_f32 v[164:165], v[148:149], v[164:165]
	v_pk_add_f32 v[194:195], v[144:145], v[186:187]
	v_pk_add_f32 v[164:165], v[164:165], v[166:167]
	v_lshlrev_b32_e32 v140, 16, v108
	v_and_b32_e32 v141, 0xffff0000, v108
	v_lshlrev_b32_e32 v142, 16, v109
	v_and_b32_e32 v143, 0xffff0000, v109
	s_waitcnt vmcnt(1)
	v_lshlrev_b32_e32 v104, 16, v178
	v_and_b32_e32 v105, 0xffff0000, v178
	v_lshlrev_b32_e32 v106, 16, v179
	v_and_b32_e32 v107, 0xffff0000, v179
	v_pk_add_f32 v[178:179], v[194:195], v[194:195] op_sel:[0,1] op_sel_hi:[1,0]
	v_pk_add_f32 v[164:165], v[164:165], v[164:165] op_sel:[0,1] op_sel_hi:[1,0]
	v_add_f32_e32 v138, v140, v141
	v_add_f32_e32 v136, v142, v143
	v_mov_b32_e32 v179, v135
	v_mov_b32_e32 v165, v134
	v_lshlrev_b32_e32 v132, 16, v112
	v_and_b32_e32 v188, 0xffff0000, v112
	s_waitcnt vmcnt(0)
	v_lshlrev_b32_e32 v98, 16, v180
	v_and_b32_e32 v99, 0xffff0000, v180
	v_lshlrev_b32_e32 v103, 16, v181
	v_and_b32_e32 v101, 0xffff0000, v181
	v_pk_add_f32 v[180:181], v[138:139], v[136:137]
	v_pk_add_f32 v[164:165], v[164:165], v[178:179]
	v_pk_add_f32 v[196:197], v[132:133], v[188:189]
	v_pk_add_f32 v[164:165], v[164:165], v[180:181]
	v_pk_add_f32 v[190:191], v[196:197], v[196:197] op_sel:[0,1] op_sel_hi:[1,0]
	v_pk_add_f32 v[164:165], v[164:165], v[164:165] op_sel:[0,1] op_sel_hi:[1,0]
	v_add_f32_e32 v126, v128, v129
	v_add_f32_e32 v124, v130, v131
	v_mov_b32_e32 v191, v123
	v_mov_b32_e32 v165, v122
	v_lshlrev_b32_e32 v121, 16, v155
	v_lshlrev_b32_e32 v120, 16, v154
	v_and_b32_e32 v155, 0xffff0000, v155
	v_and_b32_e32 v154, 0xffff0000, v154
	v_pk_add_f32 v[196:197], v[126:127], v[124:125]
	v_pk_add_f32 v[164:165], v[164:165], v[190:191]
	v_pk_add_f32 v[192:193], v[120:121], v[154:155]
	v_pk_add_f32 v[164:165], v[164:165], v[196:197]
	v_pk_add_f32 v[192:193], v[192:193], v[192:193] op_sel:[0,1] op_sel_hi:[1,0]
	v_pk_add_f32 v[164:165], v[164:165], v[164:165] op_sel:[0,1] op_sel_hi:[1,0]
	v_add_f32_e32 v114, v116, v117
	v_add_f32_e32 v112, v118, v119
	v_mov_b32_e32 v193, v111
	v_mov_b32_e32 v165, v110
	v_lshlrev_b32_e32 v109, 16, v177
	v_lshlrev_b32_e32 v108, 16, v176
	v_and_b32_e32 v177, 0xffff0000, v177
	v_and_b32_e32 v176, 0xffff0000, v176
	v_pk_add_f32 v[198:199], v[114:115], v[112:113]
	v_pk_add_f32 v[164:165], v[164:165], v[192:193]
	v_pk_add_f32 v[194:195], v[108:109], v[176:177]
	v_pk_add_f32 v[164:165], v[164:165], v[198:199]
	v_pk_add_f32 v[194:195], v[194:195], v[194:195] op_sel:[0,1] op_sel_hi:[1,0]
	v_pk_add_f32 v[164:165], v[164:165], v[164:165] op_sel:[0,1] op_sel_hi:[1,0]
	v_add_f32_e32 v102, v104, v105
	v_add_f32_e32 v100, v106, v107
	v_mov_b32_e32 v195, v99
	v_mov_b32_e32 v165, v98
	v_pk_add_f32 v[200:201], v[102:103], v[100:101]
	v_pk_add_f32 v[164:165], v[164:165], v[194:195]
	s_nop 0
	v_pk_add_f32 v[164:165], v[164:165], v[200:201]
	s_nop 0
	v_add_f32_e32 v100, v164, v165
	ds_bpermute_b32 v102, v168, v100
	s_waitcnt lgkmcnt(0)
	v_add_f32_e32 v100, v100, v102
	ds_bpermute_b32 v102, v169, v100
	s_waitcnt lgkmcnt(0)
	v_add_f32_e32 v100, v100, v102
	ds_bpermute_b32 v102, v170, v100
	s_waitcnt lgkmcnt(0)
	v_add_f32_e32 v100, v100, v102
	ds_bpermute_b32 v102, v171, v100
	s_waitcnt lgkmcnt(0)
	v_add_f32_e32 v100, v100, v102
	ds_bpermute_b32 v102, v172, v100
	s_waitcnt lgkmcnt(0)
	v_add_f32_e32 v100, v100, v102
	ds_bpermute_b32 v102, v173, v100
	s_waitcnt lgkmcnt(0)
	v_add_f32_e32 v100, v100, v102
	v_fmac_f32_e32 v182, 0xb9800000, v100
	v_fmac_f32_e32 v183, 0xb9800000, v100
	v_fmac_f32_e32 v163, 0xb9800000, v100
	v_fmac_f32_e32 v184, 0xb9800000, v100
	v_fmac_f32_e32 v185, 0xb9800000, v100
	v_fmac_f32_e32 v161, 0xb9800000, v100
	v_fmac_f32_e32 v162, 0xb9800000, v100
	v_fmac_f32_e32 v160, 0xb9800000, v100
	v_fmac_f32_e32 v186, 0xb9800000, v100
	v_fmac_f32_e32 v187, 0xb9800000, v100
	v_fmac_f32_e32 v145, 0xb9800000, v100
	v_fmac_f32_e32 v188, 0xb9800000, v100
	v_fmac_f32_e32 v189, 0xb9800000, v100
	v_fmac_f32_e32 v133, 0xb9800000, v100
	v_fmac_f32_e32 v154, 0xb9800000, v100
	v_fmac_f32_e32 v155, 0xb9800000, v100
	v_fmac_f32_e32 v121, 0xb9800000, v100
	v_fmac_f32_e32 v176, 0xb9800000, v100
	v_fmac_f32_e32 v177, 0xb9800000, v100
	v_fmac_f32_e32 v109, 0xb9800000, v100
	v_mov_b32_e32 v178, v163
	v_mov_b32_e32 v179, v183
	v_mov_b32_e32 v163, v182
	v_mov_b32_e32 v180, v161
	v_mov_b32_e32 v181, v185
	v_mov_b32_e32 v161, v184
	v_mov_b32_e32 v182, v145
	v_mov_b32_e32 v183, v187
	v_mov_b32_e32 v145, v186
	v_mov_b32_e32 v166, v133
	v_mov_b32_e32 v167, v189
	v_mov_b32_e32 v133, v188
	v_mov_b32_e32 v164, v121
	v_mov_b32_e32 v165, v155
	v_mov_b32_e32 v121, v154
	v_mov_b32_e32 v154, v109
	v_mov_b32_e32 v155, v177
	v_mov_b32_e32 v109, v176
	v_pk_mul_f32 v[176:177], v[178:179], v[178:179]
	v_pk_mul_f32 v[184:185], v[162:163], v[162:163]
	v_pk_mul_f32 v[186:187], v[180:181], v[180:181]
	v_pk_mul_f32 v[188:189], v[160:161], v[160:161]
	v_fmac_f32_e32 v156, 0xb9800000, v100
	v_fmac_f32_e32 v158, 0xb9800000, v100
	v_pk_mov_b32 v[226:227], v[184:185], v[176:177] op_sel:[1,0]
	v_mov_b32_e32 v185, v177
	v_pk_mov_b32 v[176:177], v[188:189], v[186:187] op_sel:[1,0]
	v_mov_b32_e32 v189, v187
	v_fmac_f32_e32 v157, 0xb9800000, v100
	v_fmac_f32_e32 v159, 0xb9800000, v100
	v_fmac_f32_e32 v151, 0xb9800000, v100
	v_fmac_f32_e32 v153, 0xb9800000, v100
	v_fmac_f32_e32 v147, 0xb9800000, v100
	v_fmac_f32_e32 v149, 0xb9800000, v100
	v_fmac_f32_e32 v144, 0xb9800000, v100
	v_fmac_f32_e32 v141, 0xb9800000, v100
	v_fmac_f32_e32 v140, 0xb9800000, v100
	v_fmac_f32_e32 v143, 0xb9800000, v100
	v_fmac_f32_e32 v142, 0xb9800000, v100
	v_fmac_f32_e32 v137, 0xb9800000, v100
	v_fmac_f32_e32 v139, 0xb9800000, v100
	v_fmac_f32_e32 v135, 0xb9800000, v100
	v_fmac_f32_e32 v134, 0xb9800000, v100
	v_fmac_f32_e32 v132, 0xb9800000, v100
	v_fmac_f32_e32 v129, 0xb9800000, v100
	v_fmac_f32_e32 v128, 0xb9800000, v100
	v_fmac_f32_e32 v131, 0xb9800000, v100
	v_fmac_f32_e32 v130, 0xb9800000, v100
	v_fmac_f32_e32 v125, 0xb9800000, v100
	v_fmac_f32_e32 v127, 0xb9800000, v100
	v_fmac_f32_e32 v123, 0xb9800000, v100
	v_fmac_f32_e32 v122, 0xb9800000, v100
	v_fmac_f32_e32 v120, 0xb9800000, v100
	v_fmac_f32_e32 v117, 0xb9800000, v100
	v_fmac_f32_e32 v116, 0xb9800000, v100
	v_fmac_f32_e32 v119, 0xb9800000, v100
	v_fmac_f32_e32 v118, 0xb9800000, v100
	v_fmac_f32_e32 v113, 0xb9800000, v100
	v_fmac_f32_e32 v115, 0xb9800000, v100
	v_fmac_f32_e32 v111, 0xb9800000, v100
	v_fmac_f32_e32 v110, 0xb9800000, v100
	v_fmac_f32_e32 v108, 0xb9800000, v100
	v_fmac_f32_e32 v105, 0xb9800000, v100
	v_fmac_f32_e32 v104, 0xb9800000, v100
	v_fmac_f32_e32 v107, 0xb9800000, v100
	v_fmac_f32_e32 v106, 0xb9800000, v100
	v_fmac_f32_e32 v101, 0xb9800000, v100
	v_fmac_f32_e32 v103, 0xb9800000, v100
	v_fmac_f32_e32 v99, 0xb9800000, v100
	v_fmac_f32_e32 v98, 0xb9800000, v100
	v_mul_f32_e32 v100, v156, v156
	v_mul_f32_e32 v102, v158, v158
	v_pk_add_f32 v[184:185], v[226:227], v[184:185]
	v_pk_add_f32 v[176:177], v[176:177], v[188:189]
	v_pk_fma_f32 v[190:191], v[156:157], v[156:157], v[100:101] op_sel_hi:[1,1,0]
	v_pk_fma_f32 v[192:193], v[158:159], v[158:159], v[102:103] op_sel_hi:[1,1,0]
	v_pk_add_f32 v[184:185], v[184:185], v[184:185] op_sel_hi:[0,1]
	v_pk_add_f32 v[176:177], v[176:177], v[176:177] op_sel_hi:[0,1]
	v_pk_mul_f32 v[194:195], v[182:183], v[182:183]
	v_pk_mul_f32 v[196:197], v[144:145], v[144:145]
	v_mul_f32_e32 v190, v149, v149
	v_mul_f32_e32 v192, v147, v147
	v_mul_f32_e32 v184, v153, v153
	v_mul_f32_e32 v176, v151, v151
	v_pk_mov_b32 v[186:187], v[196:197], v[194:195] op_sel:[1,0]
	v_mov_b32_e32 v197, v195
	v_pk_add_f32 v[188:189], v[190:191], v[192:193]
	v_pk_add_f32 v[176:177], v[184:185], v[176:177]
	v_mul_f32_e32 v112, v140, v140
	v_mul_f32_e32 v114, v142, v142
	v_pk_add_f32 v[186:187], v[186:187], v[196:197]
	v_pk_add_f32 v[176:177], v[188:189], v[176:177]
	v_pk_fma_f32 v[198:199], v[140:141], v[140:141], v[112:113] op_sel_hi:[1,1,0]
	v_pk_fma_f32 v[200:201], v[142:143], v[142:143], v[114:115] op_sel_hi:[1,1,0]
	v_pk_add_f32 v[186:187], v[186:187], v[186:187] op_sel_hi:[0,1]
	v_pk_add_f32 v[176:177], v[176:177], v[176:177] op_sel_hi:[0,1]
	v_pk_mul_f32 v[202:203], v[166:167], v[166:167]
	v_pk_mul_f32 v[204:205], v[132:133], v[132:133]
	v_mul_f32_e32 v198, v134, v134
	v_mul_f32_e32 v200, v135, v135
	v_mul_f32_e32 v186, v139, v139
	v_mul_f32_e32 v176, v137, v137
	v_pk_mov_b32 v[194:195], v[204:205], v[202:203] op_sel:[1,0]
	v_mov_b32_e32 v205, v203
	v_pk_add_f32 v[190:191], v[198:199], v[200:201]
	v_pk_add_f32 v[176:177], v[186:187], v[176:177]
	v_mul_f32_e32 v124, v128, v128
	v_mul_f32_e32 v126, v130, v130
	v_pk_add_f32 v[192:193], v[194:195], v[204:205]
	v_pk_add_f32 v[176:177], v[190:191], v[176:177]
	v_pk_fma_f32 v[206:207], v[128:129], v[128:129], v[124:125] op_sel_hi:[1,1,0]
	v_pk_fma_f32 v[208:209], v[130:131], v[130:131], v[126:127] op_sel_hi:[1,1,0]
	v_pk_add_f32 v[192:193], v[192:193], v[192:193] op_sel_hi:[0,1]
	v_pk_add_f32 v[176:177], v[176:177], v[176:177] op_sel_hi:[0,1]
	v_pk_mul_f32 v[210:211], v[164:165], v[164:165]
	v_pk_mul_f32 v[212:213], v[120:121], v[120:121]
	v_mul_f32_e32 v206, v122, v122
	v_mul_f32_e32 v208, v123, v123
	v_mul_f32_e32 v192, v127, v127
	v_mul_f32_e32 v176, v125, v125
	v_pk_mov_b32 v[202:203], v[212:213], v[210:211] op_sel:[1,0]
	v_mov_b32_e32 v213, v211
	v_pk_add_f32 v[194:195], v[206:207], v[208:209]
	v_pk_add_f32 v[176:177], v[192:193], v[176:177]
	v_mul_f32_e32 v136, v116, v116
	v_mul_f32_e32 v138, v118, v118
	v_pk_add_f32 v[196:197], v[202:203], v[212:213]
	v_pk_add_f32 v[176:177], v[194:195], v[176:177]
	v_pk_fma_f32 v[214:215], v[116:117], v[116:117], v[136:137] op_sel_hi:[1,1,0]
	v_pk_fma_f32 v[216:217], v[118:119], v[118:119], v[138:139] op_sel_hi:[1,1,0]
	v_pk_add_f32 v[196:197], v[196:197], v[196:197] op_sel_hi:[0,1]
	v_pk_add_f32 v[176:177], v[176:177], v[176:177] op_sel_hi:[0,1]
	v_pk_mul_f32 v[218:219], v[154:155], v[154:155]
	v_pk_mul_f32 v[220:221], v[108:109], v[108:109]
	v_mul_f32_e32 v214, v110, v110
	v_mul_f32_e32 v216, v111, v111
	v_mul_f32_e32 v196, v115, v115
	v_mul_f32_e32 v176, v113, v113
	v_pk_mov_b32 v[210:211], v[220:221], v[218:219] op_sel:[1,0]
	v_mov_b32_e32 v221, v219
	v_pk_add_f32 v[198:199], v[214:215], v[216:217]
	v_pk_add_f32 v[176:177], v[196:197], v[176:177]
	v_mul_f32_e32 v146, v104, v104
	v_mul_f32_e32 v148, v106, v106
	v_pk_add_f32 v[200:201], v[210:211], v[220:221]
	v_pk_add_f32 v[176:177], v[198:199], v[176:177]
	v_pk_fma_f32 v[222:223], v[104:105], v[104:105], v[146:147] op_sel_hi:[1,1,0]
	v_pk_fma_f32 v[224:225], v[106:107], v[106:107], v[148:149] op_sel_hi:[1,1,0]
	v_pk_add_f32 v[200:201], v[200:201], v[200:201] op_sel_hi:[0,1]
	v_pk_add_f32 v[176:177], v[176:177], v[176:177] op_sel_hi:[0,1]
	v_mul_f32_e32 v222, v98, v98
	v_mul_f32_e32 v224, v99, v99
	v_mul_f32_e32 v200, v103, v103
	v_mul_f32_e32 v176, v101, v101
	v_pk_add_f32 v[202:203], v[222:223], v[224:225]
	v_pk_add_f32 v[176:177], v[200:201], v[176:177]
	v_mov_b32_e32 v150, v153
	v_pk_add_f32 v[176:177], v[202:203], v[176:177]
	v_mov_b32_e32 v146, v149
	v_add_f32_e32 v100, v176, v177
	ds_bpermute_b32 v102, v168, v100
	v_mov_b32_e32 v136, v139
	s_waitcnt lgkmcnt(0)
	v_add_f32_e32 v100, v100, v102
	ds_bpermute_b32 v102, v169, v100
	s_waitcnt lgkmcnt(0)
	v_add_f32_e32 v100, v100, v102
	ds_bpermute_b32 v102, v170, v100
	s_waitcnt lgkmcnt(0)
	v_add_f32_e32 v100, v100, v102
	ds_bpermute_b32 v102, v171, v100
	s_waitcnt lgkmcnt(0)
	v_add_f32_e32 v100, v100, v102
	ds_bpermute_b32 v102, v172, v100
	s_waitcnt lgkmcnt(0)
	v_add_f32_e32 v100, v100, v102
	ds_bpermute_b32 v102, v173, v100
	s_waitcnt lgkmcnt(0)
	v_add_f32_e32 v100, v100, v102
	v_fmamk_f32 v100, v100, 0x39800000, v174
	v_mul_f32_e32 v102, 0x4f800000, v100
	v_cmp_gt_f32_e32 vcc, s3, v100
	s_nop 1
	v_cndmask_b32_e32 v100, v100, v102, vcc
	v_sqrt_f32_e32 v102, v100
	s_nop 0
	v_add_u32_e32 v112, -1, v102
	v_add_u32_e32 v114, 1, v102
	v_fma_f32 v124, -v112, v102, v100
	v_fma_f32 v126, -v114, v102, v100
	v_cmp_ge_f32_e64 s[0:1], 0, v124
	s_nop 1
	v_cndmask_b32_e64 v102, v102, v112, s[0:1]
	v_cmp_lt_f32_e64 s[0:1], 0, v126
	s_nop 1
	v_cndmask_b32_e64 v102, v102, v114, s[0:1]
	v_mul_f32_e32 v112, 0x37800000, v102
	v_cndmask_b32_e32 v102, v102, v112, vcc
	v_cmp_class_f32_e32 vcc, v100, v175
	s_nop 1
	v_cndmask_b32_e32 v100, v102, v100, vcc
	v_div_scale_f32 v102, s[0:1], v100, v100, 1.0
	v_rcp_f32_e32 v114, v102
	v_div_scale_f32 v112, vcc, 1.0, v100, 1.0
	v_fma_f32 v124, -v102, v114, 1.0
	v_fmac_f32_e32 v114, v124, v114
	v_mul_f32_e32 v124, v112, v114
	v_fma_f32 v126, -v102, v124, v112
	v_fmac_f32_e32 v124, v126, v114
	v_fma_f32 v102, -v102, v124, v112
	v_div_fmas_f32 v102, v102, v114, v124
	v_div_fixup_f32 v102, v102, v100, 1.0
	v_pk_mul_f32 v[162:163], v[162:163], v[102:103] op_sel_hi:[1,0]
	v_pk_mul_f32 v[176:177], v[178:179], v[102:103] op_sel_hi:[1,0]
	v_pk_fma_f32 v[64:65], v[0:1], v[162:163], v[64:65]
	v_pk_fma_f32 v[66:67], v[2:3], v[176:177], v[66:67]
	global_store_dwordx4 v[94:95], v[64:67], off sc1
	ds_read_b128 v[64:67], v232 offset:1024
	v_pk_mul_f32 v[162:163], v[180:181], v[102:103] op_sel_hi:[1,0]
	v_pk_mul_f32 v[160:161], v[160:161], v[102:103] op_sel_hi:[1,0]
	v_pk_mul_f32 v[158:159], v[158:159], v[102:103] op_sel_hi:[1,0]
	v_pk_mul_f32 v[156:157], v[156:157], v[102:103] op_sel_hi:[1,0]
	v_pk_mul_f32 v[148:149], v[150:151], v[102:103] op_sel_hi:[1,0]
	v_pk_mul_f32 v[146:147], v[146:147], v[102:103] op_sel_hi:[1,0]
	v_pk_mul_f32 v[144:145], v[144:145], v[102:103] op_sel_hi:[1,0]
	v_pk_mul_f32 v[142:143], v[142:143], v[102:103] op_sel_hi:[1,0]
	v_pk_mul_f32 v[140:141], v[140:141], v[102:103] op_sel_hi:[1,0]
	v_pk_mul_f32 v[136:137], v[136:137], v[102:103] op_sel_hi:[1,0]
	v_pk_mul_f32 v[134:135], v[134:135], v[102:103] op_sel_hi:[1,0]
	v_pk_mul_f32 v[132:133], v[132:133], v[102:103] op_sel_hi:[1,0]
	v_pk_mul_f32 v[130:131], v[130:131], v[102:103] op_sel_hi:[1,0]
	v_pk_mul_f32 v[128:129], v[128:129], v[102:103] op_sel_hi:[1,0]
	v_mov_b32_e32 v124, v127
	v_pk_mul_f32 v[124:125], v[124:125], v[102:103] op_sel_hi:[1,0]
	v_pk_mul_f32 v[122:123], v[122:123], v[102:103] op_sel_hi:[1,0]
	v_pk_mul_f32 v[120:121], v[120:121], v[102:103] op_sel_hi:[1,0]
	v_pk_mul_f32 v[118:119], v[118:119], v[102:103] op_sel_hi:[1,0]
	v_pk_mul_f32 v[116:117], v[116:117], v[102:103] op_sel_hi:[1,0]
	v_mov_b32_e32 v112, v115
	v_pk_mul_f32 v[112:113], v[112:113], v[102:103] op_sel_hi:[1,0]
	v_pk_mul_f32 v[110:111], v[110:111], v[102:103] op_sel_hi:[1,0]
	v_pk_mul_f32 v[108:109], v[108:109], v[102:103] op_sel_hi:[1,0]
	v_pk_mul_f32 v[106:107], v[106:107], v[102:103] op_sel_hi:[1,0]
	v_pk_mul_f32 v[104:105], v[104:105], v[102:103] op_sel_hi:[1,0]
	v_mov_b32_e32 v100, v103
	v_pk_mul_f32 v[100:101], v[100:101], v[102:103] op_sel_hi:[1,0]
	v_pk_mul_f32 v[98:99], v[98:99], v[102:103] op_sel_hi:[1,0]
	s_waitcnt lgkmcnt(0)
	v_pk_fma_f32 v[64:65], v[4:5], v[160:161], v[64:65]
	v_pk_fma_f32 v[66:67], v[6:7], v[162:163], v[66:67]
	global_store_dwordx4 v[94:95], v[64:67], off offset:1024 sc1
	ds_read_b128 v[64:67], v232 offset:2048
	s_waitcnt lgkmcnt(0)
	v_pk_fma_f32 v[64:65], v[8:9], v[156:157], v[64:65]
	v_pk_fma_f32 v[66:67], v[10:11], v[158:159], v[66:67]
	global_store_dwordx4 v[94:95], v[64:67], off offset:2048 sc1
	ds_read_b128 v[64:67], v232 offset:3072
	s_waitcnt lgkmcnt(0)
	v_pk_fma_f32 v[64:65], v[12:13], v[146:147], v[64:65]
	v_pk_fma_f32 v[66:67], v[14:15], v[148:149], v[66:67]
	global_store_dwordx4 v[94:95], v[64:67], off offset:3072 sc1
	ds_read_b128 v[64:67], v232 offset:4096
	v_add_co_u32_e32 v146, vcc, s11, v94
	v_pk_mul_f32 v[148:149], v[182:183], v[102:103] op_sel_hi:[1,0]
	s_nop 0
	v_addc_co_u32_e32 v147, vcc, 0, v95, vcc
	s_waitcnt lgkmcnt(0)
	v_pk_fma_f32 v[64:65], v[16:17], v[144:145], v[64:65]
	v_pk_fma_f32 v[66:67], v[18:19], v[148:149], v[66:67]
	global_store_dwordx4 v[146:147], v[64:67], off offset:-4096 sc1
	ds_read_b128 v[64:67], v232 offset:5120
	v_add_co_u32_e32 v144, vcc, s10, v94
	s_waitcnt lgkmcnt(0)
	v_pk_fma_f32 v[64:65], v[20:21], v[140:141], v[64:65]
	v_addc_co_u32_e32 v145, vcc, 0, v95, vcc
	v_pk_fma_f32 v[66:67], v[22:23], v[142:143], v[66:67]
	global_store_dwordx4 v[144:145], v[64:67], off offset:1024 sc1
	ds_read_b128 v[64:67], v232 offset:6144
	s_waitcnt lgkmcnt(0)
	v_pk_fma_f32 v[64:65], v[24:25], v[134:135], v[64:65]
	v_pk_fma_f32 v[66:67], v[26:27], v[136:137], v[66:67]
	global_store_dwordx4 v[144:145], v[64:67], off offset:2048 sc1
	ds_read_b128 v[64:67], v232 offset:7168
	v_pk_mul_f32 v[134:135], v[166:167], v[102:103] op_sel_hi:[1,0]
	s_waitcnt lgkmcnt(0)
	v_pk_fma_f32 v[64:65], v[28:29], v[132:133], v[64:65]
	v_pk_fma_f32 v[66:67], v[30:31], v[134:135], v[66:67]
	global_store_dwordx4 v[144:145], v[64:67], off offset:3072 sc1
	ds_read_b128 v[64:67], v232 offset:8192
	s_waitcnt lgkmcnt(0)
	v_pk_fma_f32 v[64:65], v[32:33], v[128:129], v[64:65]
	v_pk_fma_f32 v[66:67], v[34:35], v[130:131], v[66:67]
	global_store_dwordx4 v[146:147], v[64:67], off sc1
	ds_read_b128 v[64:67], v232 offset:9216
	s_waitcnt lgkmcnt(0)
	v_pk_fma_f32 v[64:65], v[36:37], v[122:123], v[64:65]
	v_pk_fma_f32 v[66:67], v[38:39], v[124:125], v[66:67]
	global_store_dwordx4 v[146:147], v[64:67], off offset:1024 sc1
	ds_read_b128 v[64:67], v232 offset:10240
	v_pk_mul_f32 v[122:123], v[164:165], v[102:103] op_sel_hi:[1,0]
	s_waitcnt lgkmcnt(0)
	v_pk_fma_f32 v[64:65], v[40:41], v[120:121], v[64:65]
	v_pk_fma_f32 v[66:67], v[42:43], v[122:123], v[66:67]
	global_store_dwordx4 v[146:147], v[64:67], off offset:2048 sc1
	ds_read_b128 v[64:67], v232 offset:11264
	s_waitcnt lgkmcnt(0)
	v_pk_fma_f32 v[64:65], v[44:45], v[116:117], v[64:65]
	v_pk_fma_f32 v[66:67], v[46:47], v[118:119], v[66:67]
	global_store_dwordx4 v[146:147], v[64:67], off offset:3072 sc1
	ds_read_b128 v[64:67], v232 offset:12288
	v_add_co_u32_e32 v116, vcc, s12, v94
	s_waitcnt lgkmcnt(0)
	v_pk_fma_f32 v[64:65], v[48:49], v[110:111], v[64:65]
	v_addc_co_u32_e32 v117, vcc, 0, v95, vcc
	v_pk_fma_f32 v[66:67], v[50:51], v[112:113], v[66:67]
	global_store_dwordx4 v[116:117], v[64:67], off sc1
	ds_read_b128 v[64:67], v232 offset:13312
	v_pk_mul_f32 v[110:111], v[154:155], v[102:103] op_sel_hi:[1,0]
	v_lshl_add_u64 v[94:95], v[94:95], 0, s[6:7]
	s_waitcnt lgkmcnt(0)
	v_pk_fma_f32 v[64:65], v[52:53], v[108:109], v[64:65]
	v_pk_fma_f32 v[66:67], v[54:55], v[110:111], v[66:67]
	global_store_dwordx4 v[116:117], v[64:67], off offset:1024 sc1
	ds_read_b128 v[64:67], v232 offset:14336
	s_waitcnt lgkmcnt(0)
	v_pk_fma_f32 v[64:65], v[56:57], v[104:105], v[64:65]
	v_pk_fma_f32 v[66:67], v[58:59], v[106:107], v[66:67]
	global_store_dwordx4 v[116:117], v[64:67], off offset:2048 sc1
	ds_read_b128 v[64:67], v232 offset:15360
	s_waitcnt lgkmcnt(0)
	v_pk_fma_f32 v[64:65], v[60:61], v[98:99], v[64:65]
	v_pk_fma_f32 v[66:67], v[62:63], v[100:101], v[66:67]
	global_store_dwordx4 v[116:117], v[64:67], off offset:3072 sc1
	s_cbranch_scc1 .LBB0_1087
